# P1 plain epilogue: separate path for unscaled tiles (no pk_mul/cndmask) on top of saddr stores
# baseline (speedup 1.0000x reference)
.LBB0_108:
	s_mov_b32 s98, 0
	v_lshl_add_u32 v146, s46, 8, v152
	s_cmpk_lg_i32 s18, 0x4c
	s_mov_b64 s[0:1], -1
	v_readlane_b32 s61, v254, 34
	s_cbranch_scc0 .LBB0_115
	s_cmp_lt_i32 s18, 60
	s_cbranch_scc0 .LBB0_111
	s_and_b32 s0, s18, -4
	s_cmp_eq_u32 s0, 36
	s_cbranch_scc0 .Lp1_fastepi
	s_lshl_b32 s78, s18, 22
	v_lshl_add_u32 v174, v146, 9, v0
	v_add_u32_e32 v174, s78, v174
	v_add_u32_e32 v175, 0x2000, v174
	v_add_u32_e32 v176, 0x4000, v174
	v_add_u32_e32 v177, 0x6000, v174
	v_add_u32_e32 v178, 0x10000, v174
	v_add_u32_e32 v179, 0x12000, v174
	v_add_u32_e32 v180, 0x14000, v174
	v_add_u32_e32 v181, 0x16000, v174
	s_mov_b32 s98, 16
	s_and_b32 s0, s18, -4
	s_cmp_eq_u32 s0, 36
	v_pk_mul_f32 v[156:157], v[72:73], s[26:27] op_sel_hi:[1,0]
	v_pk_mul_f32 v[158:159], v[70:71], s[26:27] op_sel_hi:[1,0]
	v_pk_mul_f32 v[160:161], v[68:69], s[26:27] op_sel_hi:[1,0]
	v_pk_mul_f32 v[162:163], v[66:67], s[26:27] op_sel_hi:[1,0]
	s_cselect_b64 vcc, -1, 0
	v_cndmask_b32_e32 v147, v73, v157, vcc
	v_cndmask_b32_e32 v157, v72, v156, vcc
	v_cndmask_b32_e32 v156, v71, v159, vcc
	v_cndmask_b32_e32 v158, v70, v158, vcc
	v_cndmask_b32_e32 v159, v69, v161, vcc
	v_cndmask_b32_e32 v160, v68, v160, vcc
	v_cndmask_b32_e32 v161, v67, v163, vcc
	v_cndmask_b32_e32 v162, v66, v162, vcc
	v_cvt_pk_bf16_f32 v156, v158, v156
	v_cvt_pk_bf16_f32 v157, v157, v147
	v_cvt_pk_bf16_f32 v158, v162, v161
	v_cvt_pk_bf16_f32 v159, v160, v159
	global_store_dwordx4 v174, v[156:159], s[14:15]
	s_nop 1
	v_pk_mul_f32 v[160:161], v[124:125], s[26:27] op_sel_hi:[1,0]
	v_pk_mul_f32 v[162:163], v[122:123], s[26:27] op_sel_hi:[1,0]
	v_pk_mul_f32 v[156:157], v[128:129], s[26:27] op_sel_hi:[1,0]
	v_pk_mul_f32 v[158:159], v[126:127], s[26:27] op_sel_hi:[1,0]
	v_cndmask_b32_e32 v147, v129, v157, vcc
	v_cndmask_b32_e32 v157, v128, v156, vcc
	v_cndmask_b32_e32 v156, v127, v159, vcc
	v_cndmask_b32_e32 v158, v126, v158, vcc
	v_cndmask_b32_e32 v159, v125, v161, vcc
	v_cndmask_b32_e32 v160, v124, v160, vcc
	v_cndmask_b32_e32 v161, v123, v163, vcc
	v_cndmask_b32_e32 v162, v122, v162, vcc
	v_cvt_pk_bf16_f32 v156, v158, v156
	v_cvt_pk_bf16_f32 v157, v157, v147
	v_cvt_pk_bf16_f32 v158, v162, v161
	v_cvt_pk_bf16_f32 v159, v160, v159
	global_store_dwordx4 v174, v[156:159], s[14:15] offset:256
	s_nop 1
	v_pk_mul_f32 v[162:163], v[60:61], s[26:27] op_sel_hi:[1,0]
	v_pk_mul_f32 v[164:165], v[58:59], s[26:27] op_sel_hi:[1,0]
	v_pk_mul_f32 v[156:157], v[64:65], s[26:27] op_sel_hi:[1,0]
	v_pk_mul_f32 v[158:159], v[62:63], s[26:27] op_sel_hi:[1,0]
	v_cndmask_b32_e32 v147, v65, v157, vcc
	v_cndmask_b32_e32 v157, v64, v156, vcc
	v_cndmask_b32_e32 v156, v63, v159, vcc
	v_cndmask_b32_e32 v158, v62, v158, vcc
	v_cndmask_b32_e32 v159, v61, v163, vcc
	v_cndmask_b32_e32 v162, v60, v162, vcc
	v_cndmask_b32_e32 v163, v59, v165, vcc
	v_cndmask_b32_e32 v164, v58, v164, vcc
	v_cvt_pk_bf16_f32 v156, v158, v156
	v_cvt_pk_bf16_f32 v157, v157, v147
	v_cvt_pk_bf16_f32 v158, v164, v163
	v_cvt_pk_bf16_f32 v159, v162, v159
	global_store_dwordx4 v175, v[156:159], s[14:15]
	s_nop 1
	v_pk_mul_f32 v[162:163], v[116:117], s[26:27] op_sel_hi:[1,0]
	v_pk_mul_f32 v[164:165], v[114:115], s[26:27] op_sel_hi:[1,0]
	v_pk_mul_f32 v[156:157], v[120:121], s[26:27] op_sel_hi:[1,0]
	v_pk_mul_f32 v[158:159], v[118:119], s[26:27] op_sel_hi:[1,0]
	v_cndmask_b32_e32 v147, v121, v157, vcc
	v_cndmask_b32_e32 v157, v120, v156, vcc
	v_cndmask_b32_e32 v156, v119, v159, vcc
	v_cndmask_b32_e32 v158, v118, v158, vcc
	v_cndmask_b32_e32 v159, v117, v163, vcc
	v_cndmask_b32_e32 v162, v116, v162, vcc
	v_cndmask_b32_e32 v163, v115, v165, vcc
	v_cndmask_b32_e32 v164, v114, v164, vcc
	v_cvt_pk_bf16_f32 v156, v158, v156
	v_cvt_pk_bf16_f32 v157, v157, v147
	v_cvt_pk_bf16_f32 v158, v164, v163
	v_cvt_pk_bf16_f32 v159, v162, v159
	global_store_dwordx4 v175, v[156:159], s[14:15] offset:256
	s_nop 1
	v_pk_mul_f32 v[162:163], v[48:49], s[26:27] op_sel_hi:[1,0]
	v_pk_mul_f32 v[164:165], v[46:47], s[26:27] op_sel_hi:[1,0]
	v_pk_mul_f32 v[156:157], v[52:53], s[26:27] op_sel_hi:[1,0]
	v_pk_mul_f32 v[158:159], v[50:51], s[26:27] op_sel_hi:[1,0]
	v_cndmask_b32_e32 v147, v53, v157, vcc
	v_cndmask_b32_e32 v157, v52, v156, vcc
	v_cndmask_b32_e32 v156, v51, v159, vcc
	v_cndmask_b32_e32 v158, v50, v158, vcc
	v_cndmask_b32_e32 v159, v49, v163, vcc
	v_cndmask_b32_e32 v162, v48, v162, vcc
	v_cndmask_b32_e32 v163, v47, v165, vcc
	v_cndmask_b32_e32 v164, v46, v164, vcc
	v_cvt_pk_bf16_f32 v156, v158, v156
	v_cvt_pk_bf16_f32 v157, v157, v147
	v_cvt_pk_bf16_f32 v158, v164, v163
	v_cvt_pk_bf16_f32 v159, v162, v159
	global_store_dwordx4 v176, v[156:159], s[14:15]
	s_nop 1
	v_pk_mul_f32 v[162:163], v[108:109], s[26:27] op_sel_hi:[1,0]
	v_pk_mul_f32 v[164:165], v[106:107], s[26:27] op_sel_hi:[1,0]
	v_pk_mul_f32 v[156:157], v[112:113], s[26:27] op_sel_hi:[1,0]
	v_pk_mul_f32 v[158:159], v[110:111], s[26:27] op_sel_hi:[1,0]
	v_cndmask_b32_e32 v147, v113, v157, vcc
	v_cndmask_b32_e32 v157, v112, v156, vcc
	v_cndmask_b32_e32 v156, v111, v159, vcc
	v_cndmask_b32_e32 v158, v110, v158, vcc
	v_cndmask_b32_e32 v159, v109, v163, vcc
	v_cndmask_b32_e32 v162, v108, v162, vcc
	v_cndmask_b32_e32 v163, v107, v165, vcc
	v_cndmask_b32_e32 v164, v106, v164, vcc
	v_cvt_pk_bf16_f32 v156, v158, v156
	v_cvt_pk_bf16_f32 v157, v157, v147
	v_cvt_pk_bf16_f32 v158, v164, v163
	v_cvt_pk_bf16_f32 v159, v162, v159
	global_store_dwordx4 v176, v[156:159], s[14:15] offset:256
	s_nop 1
	v_pk_mul_f32 v[160:161], v[40:41], s[26:27] op_sel_hi:[1,0]
	v_pk_mul_f32 v[162:163], v[38:39], s[26:27] op_sel_hi:[1,0]
	v_pk_mul_f32 v[156:157], v[44:45], s[26:27] op_sel_hi:[1,0]
	v_pk_mul_f32 v[158:159], v[42:43], s[26:27] op_sel_hi:[1,0]
	v_cndmask_b32_e32 v147, v45, v157, vcc
	v_cndmask_b32_e32 v157, v44, v156, vcc
	v_cndmask_b32_e32 v156, v43, v159, vcc
	v_cndmask_b32_e32 v158, v42, v158, vcc
	v_cndmask_b32_e32 v159, v41, v161, vcc
	v_cndmask_b32_e32 v160, v40, v160, vcc
	v_cndmask_b32_e32 v161, v39, v163, vcc
	v_cndmask_b32_e32 v162, v38, v162, vcc
	v_cvt_pk_bf16_f32 v156, v158, v156
	v_cvt_pk_bf16_f32 v157, v157, v147
	v_cvt_pk_bf16_f32 v158, v162, v161
	v_cvt_pk_bf16_f32 v159, v160, v159
	global_store_dwordx4 v177, v[156:159], s[14:15]
	s_nop 1
	v_pk_mul_f32 v[160:161], v[100:101], s[26:27] op_sel_hi:[1,0]
	v_pk_mul_f32 v[162:163], v[98:99], s[26:27] op_sel_hi:[1,0]
	v_pk_mul_f32 v[156:157], v[104:105], s[26:27] op_sel_hi:[1,0]
	v_pk_mul_f32 v[158:159], v[102:103], s[26:27] op_sel_hi:[1,0]
	v_cndmask_b32_e32 v147, v105, v157, vcc
	v_cndmask_b32_e32 v157, v104, v156, vcc
	v_cndmask_b32_e32 v156, v103, v159, vcc
	v_cndmask_b32_e32 v158, v102, v158, vcc
	v_cndmask_b32_e32 v159, v101, v161, vcc
	v_cndmask_b32_e32 v160, v100, v160, vcc
	v_cndmask_b32_e32 v161, v99, v163, vcc
	v_cndmask_b32_e32 v162, v98, v162, vcc
	v_cvt_pk_bf16_f32 v156, v158, v156
	v_cvt_pk_bf16_f32 v157, v157, v147
	v_cvt_pk_bf16_f32 v158, v162, v161
	v_cvt_pk_bf16_f32 v159, v160, v159
	global_store_dwordx4 v177, v[156:159], s[14:15] offset:256
	s_nop 1
	v_pk_mul_f32 v[160:161], v[28:29], s[26:27] op_sel_hi:[1,0]
	v_pk_mul_f32 v[156:157], v[32:33], s[26:27] op_sel_hi:[1,0]
	v_pk_mul_f32 v[158:159], v[30:31], s[26:27] op_sel_hi:[1,0]
	v_pk_mul_f32 v[162:163], v[26:27], s[26:27] op_sel_hi:[1,0]
	v_cndmask_b32_e32 v147, v33, v157, vcc
	v_cndmask_b32_e32 v157, v32, v156, vcc
	v_cndmask_b32_e32 v156, v31, v159, vcc
	v_cndmask_b32_e32 v159, v29, v161, vcc
	v_cndmask_b32_e32 v160, v28, v160, vcc
	v_cndmask_b32_e32 v158, v30, v158, vcc
	v_cndmask_b32_e32 v161, v27, v163, vcc
	v_cndmask_b32_e32 v162, v26, v162, vcc
	v_cvt_pk_bf16_f32 v159, v160, v159
	v_cvt_pk_bf16_f32 v156, v158, v156
	v_cvt_pk_bf16_f32 v157, v157, v147
	v_cvt_pk_bf16_f32 v158, v162, v161
	global_store_dwordx4 v178, v[156:159], s[14:15]
	s_nop 1
	v_pk_mul_f32 v[160:161], v[92:93], s[26:27] op_sel_hi:[1,0]
	v_pk_mul_f32 v[162:163], v[90:91], s[26:27] op_sel_hi:[1,0]
	v_pk_mul_f32 v[156:157], v[96:97], s[26:27] op_sel_hi:[1,0]
	v_pk_mul_f32 v[158:159], v[94:95], s[26:27] op_sel_hi:[1,0]
	v_cndmask_b32_e32 v147, v97, v157, vcc
	v_cndmask_b32_e32 v157, v96, v156, vcc
	v_cndmask_b32_e32 v156, v95, v159, vcc
	v_cndmask_b32_e32 v158, v94, v158, vcc
	v_cndmask_b32_e32 v159, v93, v161, vcc
	v_cndmask_b32_e32 v160, v92, v160, vcc
	v_cndmask_b32_e32 v161, v91, v163, vcc
	v_cndmask_b32_e32 v162, v90, v162, vcc
	v_cvt_pk_bf16_f32 v156, v158, v156
	v_cvt_pk_bf16_f32 v157, v157, v147
	v_cvt_pk_bf16_f32 v158, v162, v161
	v_cvt_pk_bf16_f32 v159, v160, v159
	global_store_dwordx4 v178, v[156:159], s[14:15] offset:256
	s_nop 1
	v_pk_mul_f32 v[160:161], v[20:21], s[26:27] op_sel_hi:[1,0]
	v_pk_mul_f32 v[156:157], v[24:25], s[26:27] op_sel_hi:[1,0]
	v_pk_mul_f32 v[158:159], v[22:23], s[26:27] op_sel_hi:[1,0]
	v_pk_mul_f32 v[162:163], v[18:19], s[26:27] op_sel_hi:[1,0]
	v_cndmask_b32_e32 v147, v25, v157, vcc
	v_cndmask_b32_e32 v157, v24, v156, vcc
	v_cndmask_b32_e32 v156, v23, v159, vcc
	v_cndmask_b32_e32 v159, v21, v161, vcc
	v_cndmask_b32_e32 v160, v20, v160, vcc
	v_cndmask_b32_e32 v158, v22, v158, vcc
	v_cndmask_b32_e32 v161, v19, v163, vcc
	v_cndmask_b32_e32 v162, v18, v162, vcc
	v_cvt_pk_bf16_f32 v159, v160, v159
	v_cvt_pk_bf16_f32 v156, v158, v156
	v_cvt_pk_bf16_f32 v157, v157, v147
	v_cvt_pk_bf16_f32 v158, v162, v161
	global_store_dwordx4 v179, v[156:159], s[14:15]
	s_nop 1
	v_pk_mul_f32 v[160:161], v[84:85], s[26:27] op_sel_hi:[1,0]
	v_pk_mul_f32 v[162:163], v[82:83], s[26:27] op_sel_hi:[1,0]
	v_pk_mul_f32 v[156:157], v[88:89], s[26:27] op_sel_hi:[1,0]
	v_pk_mul_f32 v[158:159], v[86:87], s[26:27] op_sel_hi:[1,0]
	v_cndmask_b32_e32 v147, v89, v157, vcc
	v_cndmask_b32_e32 v157, v88, v156, vcc
	v_cndmask_b32_e32 v156, v87, v159, vcc
	v_cndmask_b32_e32 v158, v86, v158, vcc
	v_cndmask_b32_e32 v159, v85, v161, vcc
	v_cndmask_b32_e32 v160, v84, v160, vcc
	v_cndmask_b32_e32 v161, v83, v163, vcc
	v_cndmask_b32_e32 v162, v82, v162, vcc
	v_cvt_pk_bf16_f32 v156, v158, v156
	v_cvt_pk_bf16_f32 v157, v157, v147
	v_cvt_pk_bf16_f32 v158, v162, v161
	v_cvt_pk_bf16_f32 v159, v160, v159
	global_store_dwordx4 v179, v[156:159], s[14:15] offset:256
	s_nop 1
	v_pk_mul_f32 v[160:161], v[12:13], s[26:27] op_sel_hi:[1,0]
	v_pk_mul_f32 v[156:157], v[16:17], s[26:27] op_sel_hi:[1,0]
	v_pk_mul_f32 v[158:159], v[14:15], s[26:27] op_sel_hi:[1,0]
	v_pk_mul_f32 v[162:163], v[10:11], s[26:27] op_sel_hi:[1,0]
	v_cndmask_b32_e32 v147, v17, v157, vcc
	v_cndmask_b32_e32 v157, v16, v156, vcc
	v_cndmask_b32_e32 v156, v15, v159, vcc
	v_cndmask_b32_e32 v159, v13, v161, vcc
	v_cndmask_b32_e32 v160, v12, v160, vcc
	v_cndmask_b32_e32 v158, v14, v158, vcc
	v_cndmask_b32_e32 v161, v11, v163, vcc
	v_cndmask_b32_e32 v162, v10, v162, vcc
	v_cvt_pk_bf16_f32 v159, v160, v159
	v_cvt_pk_bf16_f32 v156, v158, v156
	v_cvt_pk_bf16_f32 v157, v157, v147
	v_cvt_pk_bf16_f32 v158, v162, v161
	global_store_dwordx4 v180, v[156:159], s[14:15]
	s_nop 1
	v_pk_mul_f32 v[160:161], v[76:77], s[26:27] op_sel_hi:[1,0]
	v_pk_mul_f32 v[162:163], v[74:75], s[26:27] op_sel_hi:[1,0]
	v_pk_mul_f32 v[156:157], v[80:81], s[26:27] op_sel_hi:[1,0]
	v_pk_mul_f32 v[158:159], v[78:79], s[26:27] op_sel_hi:[1,0]
	v_cndmask_b32_e32 v147, v81, v157, vcc
	v_cndmask_b32_e32 v157, v80, v156, vcc
	v_cndmask_b32_e32 v156, v79, v159, vcc
	v_cndmask_b32_e32 v158, v78, v158, vcc
	v_cndmask_b32_e32 v159, v77, v161, vcc
	v_cndmask_b32_e32 v160, v76, v160, vcc
	v_cndmask_b32_e32 v161, v75, v163, vcc
	v_cndmask_b32_e32 v162, v74, v162, vcc
	v_cvt_pk_bf16_f32 v156, v158, v156
	v_cvt_pk_bf16_f32 v157, v157, v147
	v_cvt_pk_bf16_f32 v158, v162, v161
	v_cvt_pk_bf16_f32 v159, v160, v159
	global_store_dwordx4 v180, v[156:159], s[14:15] offset:256
	s_nop 1
	v_pk_mul_f32 v[150:151], v[8:9], s[26:27] op_sel_hi:[1,0]
	v_pk_mul_f32 v[156:157], v[6:7], s[26:27] op_sel_hi:[1,0]
	v_pk_mul_f32 v[158:159], v[4:5], s[26:27] op_sel_hi:[1,0]
	v_pk_mul_f32 v[162:163], v[2:3], s[26:27] op_sel_hi:[1,0]
	v_cndmask_b32_e32 v147, v9, v151, vcc
	v_cndmask_b32_e32 v150, v8, v150, vcc
	v_cndmask_b32_e32 v151, v7, v157, vcc
	v_cndmask_b32_e32 v156, v6, v156, vcc
	v_cndmask_b32_e32 v159, v5, v159, vcc
	v_cndmask_b32_e32 v164, v4, v158, vcc
	v_cndmask_b32_e32 v158, v3, v163, vcc
	v_cndmask_b32_e32 v162, v2, v162, vcc
	v_cvt_pk_bf16_f32 v156, v156, v151
	v_cvt_pk_bf16_f32 v157, v150, v147
	v_cvt_pk_bf16_f32 v158, v162, v158
	v_cvt_pk_bf16_f32 v159, v164, v159
	global_store_dwordx4 v181, v[156:159], s[14:15]
	s_nop 1
	v_pk_mul_f32 v[148:149], v[56:57], s[26:27] op_sel_hi:[1,0]
	v_pk_mul_f32 v[150:151], v[54:55], s[26:27] op_sel_hi:[1,0]
	v_pk_mul_f32 v[156:157], v[36:37], s[26:27] op_sel_hi:[1,0]
	v_pk_mul_f32 v[158:159], v[34:35], s[26:27] op_sel_hi:[1,0]
	v_cndmask_b32_e32 v147, v57, v149, vcc
	v_cndmask_b32_e32 v149, v56, v148, vcc
	v_cndmask_b32_e32 v148, v55, v151, vcc
	v_cndmask_b32_e32 v150, v54, v150, vcc
	v_cndmask_b32_e32 v151, v37, v157, vcc
	v_cndmask_b32_e32 v156, v36, v156, vcc
	v_cndmask_b32_e32 v157, v35, v159, vcc
	v_cndmask_b32_e32 v158, v34, v158, vcc
	v_cvt_pk_bf16_f32 v148, v150, v148
	v_cvt_pk_bf16_f32 v149, v149, v147
	v_cvt_pk_bf16_f32 v150, v158, v157
	v_cvt_pk_bf16_f32 v151, v156, v151
	global_store_dwordx4 v181, v[148:151], s[14:15] offset:256
	s_nop 1
	s_mov_b64 s[0:1], 0
	s_branch .LBB0_111
.Lp1_fastepi:
	s_lshl_b32 s78, s18, 22
	v_lshl_add_u32 v174, v146, 9, v0
	v_add_u32_e32 v174, s78, v174
	v_add_u32_e32 v175, 0x2000, v174
	v_add_u32_e32 v176, 0x4000, v174
	v_add_u32_e32 v177, 0x6000, v174
	v_add_u32_e32 v178, 0x10000, v174
	v_add_u32_e32 v179, 0x12000, v174
	v_add_u32_e32 v180, 0x14000, v174
	v_add_u32_e32 v181, 0x16000, v174
	s_mov_b32 s98, 16
	s_and_b32 s0, s18, -4
	s_cmp_eq_u32 s0, 36
	v_cvt_pk_bf16_f32 v156, v70, v71
	v_cvt_pk_bf16_f32 v157, v72, v73
	v_cvt_pk_bf16_f32 v158, v66, v67
	v_cvt_pk_bf16_f32 v159, v68, v69
	global_store_dwordx4 v174, v[156:159], s[14:15]
	s_nop 1
	v_cvt_pk_bf16_f32 v156, v126, v127
	v_cvt_pk_bf16_f32 v157, v128, v129
	v_cvt_pk_bf16_f32 v158, v122, v123
	v_cvt_pk_bf16_f32 v159, v124, v125
	global_store_dwordx4 v174, v[156:159], s[14:15] offset:256
	s_nop 1
	v_cvt_pk_bf16_f32 v156, v62, v63
	v_cvt_pk_bf16_f32 v157, v64, v65
	v_cvt_pk_bf16_f32 v158, v58, v59
	v_cvt_pk_bf16_f32 v159, v60, v61
	global_store_dwordx4 v175, v[156:159], s[14:15]
	s_nop 1
	v_cvt_pk_bf16_f32 v156, v118, v119
	v_cvt_pk_bf16_f32 v157, v120, v121
	v_cvt_pk_bf16_f32 v158, v114, v115
	v_cvt_pk_bf16_f32 v159, v116, v117
	global_store_dwordx4 v175, v[156:159], s[14:15] offset:256
	s_nop 1
	v_cvt_pk_bf16_f32 v156, v50, v51
	v_cvt_pk_bf16_f32 v157, v52, v53
	v_cvt_pk_bf16_f32 v158, v46, v47
	v_cvt_pk_bf16_f32 v159, v48, v49
	global_store_dwordx4 v176, v[156:159], s[14:15]
	s_nop 1
	v_cvt_pk_bf16_f32 v156, v110, v111
	v_cvt_pk_bf16_f32 v157, v112, v113
	v_cvt_pk_bf16_f32 v158, v106, v107
	v_cvt_pk_bf16_f32 v159, v108, v109
	global_store_dwordx4 v176, v[156:159], s[14:15] offset:256
	s_nop 1
	v_cvt_pk_bf16_f32 v156, v42, v43
	v_cvt_pk_bf16_f32 v157, v44, v45
	v_cvt_pk_bf16_f32 v158, v38, v39
	v_cvt_pk_bf16_f32 v159, v40, v41
	global_store_dwordx4 v177, v[156:159], s[14:15]
	s_nop 1
	v_cvt_pk_bf16_f32 v156, v102, v103
	v_cvt_pk_bf16_f32 v157, v104, v105
	v_cvt_pk_bf16_f32 v158, v98, v99
	v_cvt_pk_bf16_f32 v159, v100, v101
	global_store_dwordx4 v177, v[156:159], s[14:15] offset:256
	s_nop 1
	v_cvt_pk_bf16_f32 v159, v28, v29
	v_cvt_pk_bf16_f32 v156, v30, v31
	v_cvt_pk_bf16_f32 v157, v32, v33
	v_cvt_pk_bf16_f32 v158, v26, v27
	global_store_dwordx4 v178, v[156:159], s[14:15]
	s_nop 1
	v_cvt_pk_bf16_f32 v156, v94, v95
	v_cvt_pk_bf16_f32 v157, v96, v97
	v_cvt_pk_bf16_f32 v158, v90, v91
	v_cvt_pk_bf16_f32 v159, v92, v93
	global_store_dwordx4 v178, v[156:159], s[14:15] offset:256
	s_nop 1
	v_cvt_pk_bf16_f32 v159, v20, v21
	v_cvt_pk_bf16_f32 v156, v22, v23
	v_cvt_pk_bf16_f32 v157, v24, v25
	v_cvt_pk_bf16_f32 v158, v18, v19
	global_store_dwordx4 v179, v[156:159], s[14:15]
	s_nop 1
	v_cvt_pk_bf16_f32 v156, v86, v87
	v_cvt_pk_bf16_f32 v157, v88, v89
	v_cvt_pk_bf16_f32 v158, v82, v83
	v_cvt_pk_bf16_f32 v159, v84, v85
	global_store_dwordx4 v179, v[156:159], s[14:15] offset:256
	s_nop 1
	v_cvt_pk_bf16_f32 v159, v12, v13
	v_cvt_pk_bf16_f32 v156, v14, v15
	v_cvt_pk_bf16_f32 v157, v16, v17
	v_cvt_pk_bf16_f32 v158, v10, v11
	global_store_dwordx4 v180, v[156:159], s[14:15]
	s_nop 1
	v_cvt_pk_bf16_f32 v156, v78, v79
	v_cvt_pk_bf16_f32 v157, v80, v81
	v_cvt_pk_bf16_f32 v158, v74, v75
	v_cvt_pk_bf16_f32 v159, v76, v77
	global_store_dwordx4 v180, v[156:159], s[14:15] offset:256
	s_nop 1
	v_cvt_pk_bf16_f32 v156, v6, v7
	v_cvt_pk_bf16_f32 v157, v8, v9
	v_cvt_pk_bf16_f32 v158, v2, v3
	v_cvt_pk_bf16_f32 v159, v4, v5
	global_store_dwordx4 v181, v[156:159], s[14:15]
	s_nop 1
	v_cvt_pk_bf16_f32 v148, v54, v55
	v_cvt_pk_bf16_f32 v149, v56, v57
	v_cvt_pk_bf16_f32 v150, v34, v35
	v_cvt_pk_bf16_f32 v151, v36, v37
	global_store_dwordx4 v181, v[148:151], s[14:15] offset:256
	s_nop 1
	s_mov_b64 s[0:1], 0
